# v94 + attention steady loop: step-end barrier waits lgkmcnt(8) (next step's K-fragment reads stay in flight across the barrier)
# speedup vs baseline: 1.0051x; 1.0051x over previous
; #define WAIT_BAR(N) asm volatile("s_waitcnt vmcnt(" #N ") lgkmcnt(0)\n\ts_barrier" ::: "memory")
; #define RESC() do { if (!FIXM && resc) { asm volatile("s_waitcnt lgkmcnt(0)" ::: "memory"); \
;       _Pragma("unroll") for (int d_ = 0; d_ < 2; ++d_) _Pragma("unroll") for (int r = 0; r < 16; ++r) o[d_][r] *= wsf[crow(r, hi)]; } } while (0)
; #define ROT() do { sl_prev = sl_cur; sl_cur = sl_next; sl_next = (sl_next == (NSLOT - 1) * SLOTB) ? 0 : sl_next + SLOTB; } while (0)
; template <int THRL, bool FIXM> __device__ __forceinline__ bool attn_unit(const h16* Qrows, const h16* __restrict__ Kh, const h16* __restrict__ Vh, const int NT, h16* Yrows, const h16* BZrows, char* shm, const int tid, const float mfix, ...
;     ...
;   int t = 1;
;   for (; t + 5 < NT; t += 2) {
;     STEP(pB0, pB1, pA0, pA1, t, true, true, true);     WAIT_BAR(2); RESC(); ROT();
;     STEP(pA0, pA1, pB0, pB1, t + 1, true, true, true); WAIT_BAR(2); RESC(); ROT();
;   }
.LBB0_77:
	v_add_u32_e32 v0, s44, v233
	ds_read_b64_tr_b16 v[62:63], v0 offset:24576
	ds_read_b64_tr_b16 v[64:65], v0 offset:25088
	v_add_f32_e32 v51, v82, v83
	v_add_f32_e32 v51, v84, v51
	v_add_f32_e32 v51, v85, v51
	v_add_f32_e32 v51, v86, v51
	v_add_f32_e32 v51, v87, v51
	v_cvt_pk_f16_f32 v160, v82, v83
	v_cvt_pk_f16_f32 v161, v84, v85
	s_waitcnt lgkmcnt(9)
	v_mfma_f32_32x32x16_f16 v[114:129], v[192:195], v[144:147], v[2:17]
	ds_read_b64_tr_b16 v[82:83], v0 offset:28672
	ds_read_b64_tr_b16 v[84:85], v0 offset:29184
	v_add_f32_e32 v51, v88, v51
	v_add_f32_e32 v51, v89, v51
	v_add_f32_e32 v51, v90, v51
	v_add_f32_e32 v51, v91, v51
	v_cvt_pk_f16_f32 v162, v86, v87
	v_cvt_pk_f16_f32 v163, v88, v89
	s_waitcnt lgkmcnt(10)
	v_mfma_f32_32x32x16_f16 v[98:113], v[188:191], v[144:147], v[2:17]
	ds_read_b64_tr_b16 v[86:87], v0 offset:25600
	ds_read_b64_tr_b16 v[88:89], v0 offset:26112
	v_add_f32_e32 v51, v92, v51
	v_add_f32_e32 v51, v93, v51
	v_add_f32_e32 v51, v94, v51
	v_add_f32_e32 v51, v95, v51
	v_cvt_pk_f16_f32 v156, v90, v91
	v_cvt_pk_f16_f32 v157, v92, v93
	s_waitcnt lgkmcnt(11)
	v_mfma_f32_32x32x16_f16 v[114:129], v[184:187], v[140:143], v[114:129]
	ds_read_b64_tr_b16 v[90:91], v0 offset:29696
	ds_read_b64_tr_b16 v[92:93], v0 offset:30208
	v_add_f32_e32 v51, v96, v51
	v_add_f32_e32 v51, v97, v51
	v_add_f32_e32 v51, v66, v51
	v_add_f32_e32 v51, v67, v51
	v_cvt_pk_f16_f32 v158, v94, v95
	v_cvt_pk_f16_f32 v159, v96, v97
	s_waitcnt lgkmcnt(12)
	v_mfma_f32_32x32x16_f16 v[98:113], v[180:183], v[140:143], v[98:113]
	ds_read_b64_tr_b16 v[94:95], v0 offset:26624
	ds_read_b64_tr_b16 v[96:97], v0 offset:27136
	v_add_f32_e32 v51, v68, v51
	v_add_f32_e32 v51, v69, v51
	v_add_f32_e32 v51, v70, v51
	v_add_f32_e32 v51, v71, v51
	v_cvt_pk_f16_f32 v152, v66, v67
	v_cvt_pk_f16_f32 v153, v68, v69
	s_waitcnt lgkmcnt(13)
	v_mfma_f32_32x32x16_f16 v[114:129], v[176:179], v[136:139], v[114:129]
	ds_read_b64_tr_b16 v[66:67], v0 offset:30720
	ds_read_b64_tr_b16 v[68:69], v0 offset:31232
	v_add_f32_e32 v51, v72, v51
	v_add_f32_e32 v51, v73, v51
	v_add_f32_e32 v51, v74, v51
	v_add_f32_e32 v51, v75, v51
	v_cvt_pk_f16_f32 v154, v70, v71
	v_cvt_pk_f16_f32 v155, v72, v73
	s_waitcnt lgkmcnt(14)
	v_mfma_f32_32x32x16_f16 v[98:113], v[172:175], v[136:139], v[98:113]
	ds_read_b64_tr_b16 v[70:71], v0 offset:27648
	ds_read_b64_tr_b16 v[72:73], v0 offset:28160
	v_add_f32_e32 v51, v76, v51
	v_add_f32_e32 v51, v77, v51
	v_add_f32_e32 v51, v78, v51
	v_add_f32_e32 v51, v79, v51
	v_cvt_pk_f16_f32 v148, v74, v75
	v_cvt_pk_f16_f32 v149, v76, v77
	s_waitcnt lgkmcnt(14)
	v_mfma_f32_32x32x16_f16 v[114:129], v[168:171], v[132:135], v[114:129]
	ds_read_b64_tr_b16 v[74:75], v0 offset:31744
	ds_read_b64_tr_b16 v[76:77], v0 offset:32256
	v_add_f32_e32 v0, v80, v51
	v_add_f32_e32 v0, v81, v0
	v_add_f32_e32 v0, 0, v0
	v_cvt_pk_f16_f32 v150, v78, v79
	v_cvt_pk_f16_f32 v151, v80, v81
	v_mfma_f32_32x32x16_f16 v[98:113], v[164:167], v[132:135], v[98:113]
	v_lshl_add_u64 v[58:59], v[56:57], 0, s[2:3]
	v_add_f32_e32 v0, v50, v0
	v_lshl_add_u64 v[50:51], v[58:59], 0, s[46:47]
	s_add_i32 s43, s42, s97
	s_mov_b32 s44, m0
	s_mov_b32 m0, s43
	s_nop 0
	global_load_lds_dwordx4 v[50:51], off
	s_mov_b32 m0, s44
	v_lshl_add_u64 v[60:61], v[54:55], 0, s[2:3]
	v_lshl_add_u64 v[50:51], v[60:61], 0, s[36:37]
	s_add_i32 s43, s25, s83
	s_mov_b32 s44, m0
	s_mov_b32 m0, s43
	s_nop 0
	global_load_lds_dwordx4 v[50:51], off
	s_mov_b32 m0, s44
	s_waitcnt lgkmcnt(14)
	v_mfma_f32_32x32x16_f16 v[18:33], v[160:163], v[62:65], v[18:33]
	v_exp_f32_e32 v114, v114
	v_exp_f32_e32 v115, v115
	v_exp_f32_e32 v116, v116
	v_exp_f32_e32 v117, v117
	s_waitcnt lgkmcnt(12)
	v_mfma_f32_32x32x16_f16 v[34:49], v[160:163], v[82:85], v[34:49]
	v_exp_f32_e32 v118, v118
	v_exp_f32_e32 v119, v119
	v_exp_f32_e32 v120, v120
	v_exp_f32_e32 v121, v121
	v_add_u32_e32 v50, s25, v219
	ds_read_b128 v[62:65], v50
	ds_read_b128 v[164:167], v50 offset:512
	s_waitcnt lgkmcnt(12)
	v_mfma_f32_32x32x16_f16 v[18:33], v[156:159], v[86:89], v[18:33]
	v_exp_f32_e32 v122, v122
	v_exp_f32_e32 v123, v123
	v_exp_f32_e32 v124, v124
	v_exp_f32_e32 v125, v125
	ds_read_b128 v[168:171], v50 offset:2048
	ds_read_b128 v[172:175], v50 offset:2560
	s_waitcnt lgkmcnt(12)
	v_mfma_f32_32x32x16_f16 v[34:49], v[156:159], v[90:93], v[34:49]
	v_exp_f32_e32 v126, v126
	v_exp_f32_e32 v127, v127
	v_exp_f32_e32 v128, v128
	v_exp_f32_e32 v129, v129
	ds_read_b128 v[176:179], v50 offset:4096
	ds_read_b128 v[180:183], v50 offset:4608
	s_waitcnt lgkmcnt(12)
	v_mfma_f32_32x32x16_f16 v[18:33], v[152:155], v[94:97], v[18:33]
	v_exp_f32_e32 v98, v98
	v_exp_f32_e32 v99, v99
	v_exp_f32_e32 v100, v100
	v_exp_f32_e32 v101, v101
	ds_read_b128 v[184:187], v50 offset:6144
	ds_read_b128 v[50:53], v50 offset:6656
	s_waitcnt lgkmcnt(12)
	v_mfma_f32_32x32x16_f16 v[34:49], v[152:155], v[66:69], v[34:49]
	v_exp_f32_e32 v102, v102
	v_exp_f32_e32 v103, v103
	v_exp_f32_e32 v104, v104
	v_exp_f32_e32 v105, v105
	s_waitcnt lgkmcnt(10)
	v_mfma_f32_32x32x16_f16 v[18:33], v[148:151], v[70:73], v[18:33]
	v_exp_f32_e32 v106, v106
	v_exp_f32_e32 v107, v107
	v_exp_f32_e32 v108, v108
	v_exp_f32_e32 v109, v109
	s_waitcnt lgkmcnt(8)
	v_mfma_f32_32x32x16_f16 v[34:49], v[148:151], v[74:77], v[34:49]
	v_exp_f32_e32 v110, v110
	v_exp_f32_e32 v111, v111
	v_exp_f32_e32 v112, v112
	v_exp_f32_e32 v113, v113
	s_waitcnt vmcnt(2) lgkmcnt(8)
	s_barrier
; #define WAIT_BAR(N) asm volatile("s_waitcnt vmcnt(" #N ") lgkmcnt(0)\n\ts_barrier" ::: "memory")
; #define RESC() do { if (!FIXM && resc) { asm volatile("s_waitcnt lgkmcnt(0)" ::: "memory"); \
;       _Pragma("unroll") for (int d_ = 0; d_ < 2; ++d_) _Pragma("unroll") for (int r = 0; r < 16; ++r) o[d_][r] *= wsf[crow(r, hi)]; } } while (0)
; #define ROT() do { sl_prev = sl_cur; sl_cur = sl_next; sl_next = (sl_next == (NSLOT - 1) * SLOTB) ? 0 : sl_next + SLOTB; } while (0)
; template <int THRL, bool FIXM> __device__ __forceinline__ bool attn_unit(const h16* Qrows, const h16* __restrict__ Kh, const h16* __restrict__ Vh, const int NT, h16* Yrows, const h16* BZrows, char* shm, const int tid, const float mfix, ...
;     ...
;   int t = 1;
;   for (; t + 5 < NT; t += 2) {
;     STEP(pB0, pB1, pA0, pA1, t, true, true, true);     WAIT_BAR(2); RESC(); ROT();
;     STEP(pA0, pA1, pB0, pB1, t + 1, true, true, true); WAIT_BAR(2); RESC(); ROT();
;   }
	s_add_i32 s43, s25, 0x2000
	s_cmpk_lg_i32 s25, 0x4000
	s_cselect_b32 s43, s43, 0
	v_add_u32_e32 v192, s42, v233
	ds_read_b64_tr_b16 v[188:189], v192 offset:24576
	ds_read_b64_tr_b16 v[190:191], v192 offset:25088
	s_waitcnt lgkmcnt(9)
	v_mfma_f32_32x32x16_f16 v[82:97], v[62:65], v[144:147], v[2:17]
	v_add_f32_e32 v66, v114, v115
	v_add_f32_e32 v66, v116, v66
	v_add_f32_e32 v66, v117, v66
	v_add_f32_e32 v66, v118, v66
	v_add_f32_e32 v66, v119, v66
	v_cvt_pk_f16_f32 v160, v114, v115
	v_cvt_pk_f16_f32 v161, v116, v117
	ds_read_b64_tr_b16 v[62:63], v192 offset:28672
	ds_read_b64_tr_b16 v[64:65], v192 offset:29184
	v_add_f32_e32 v66, v120, v66
	v_add_f32_e32 v66, v121, v66
	v_add_f32_e32 v66, v122, v66
	v_add_f32_e32 v148, v123, v66
	s_waitcnt lgkmcnt(10)
	v_mfma_f32_32x32x16_f16 v[66:81], v[164:167], v[144:147], v[2:17]
	v_cvt_pk_f16_f32 v162, v118, v119
	v_cvt_pk_f16_f32 v163, v120, v121
	ds_read_b64_tr_b16 v[114:115], v192 offset:25600
	ds_read_b64_tr_b16 v[116:117], v192 offset:26112
	s_waitcnt lgkmcnt(11)
	v_mfma_f32_32x32x16_f16 v[82:97], v[168:171], v[140:143], v[82:97]
	v_add_f32_e32 v118, v124, v148
	v_add_f32_e32 v118, v125, v118
	v_add_f32_e32 v118, v126, v118
	v_add_f32_e32 v148, v127, v118
	v_cvt_pk_f16_f32 v156, v122, v123
	v_cvt_pk_f16_f32 v157, v124, v125
	ds_read_b64_tr_b16 v[118:119], v192 offset:29696
	ds_read_b64_tr_b16 v[120:121], v192 offset:30208
	s_waitcnt lgkmcnt(12)
	v_mfma_f32_32x32x16_f16 v[66:81], v[172:175], v[140:143], v[66:81]
	v_add_f32_e32 v122, v128, v148
	v_add_f32_e32 v122, v129, v122
	v_add_f32_e32 v122, v98, v122
	v_add_f32_e32 v148, v99, v122
	v_cvt_pk_f16_f32 v158, v126, v127
	v_cvt_pk_f16_f32 v159, v128, v129
	ds_read_b64_tr_b16 v[122:123], v192 offset:26624
	ds_read_b64_tr_b16 v[124:125], v192 offset:27136
	s_waitcnt lgkmcnt(13)
	v_mfma_f32_32x32x16_f16 v[82:97], v[176:179], v[136:139], v[82:97]
	v_add_f32_e32 v126, v100, v148
	v_add_f32_e32 v126, v101, v126
	v_add_f32_e32 v126, v102, v126
	v_add_f32_e32 v126, v103, v126
	v_cvt_pk_f16_f32 v152, v98, v99
	v_cvt_pk_f16_f32 v153, v100, v101
	ds_read_b64_tr_b16 v[98:99], v192 offset:30720
	ds_read_b64_tr_b16 v[100:101], v192 offset:31232
	s_waitcnt lgkmcnt(14)
	v_mfma_f32_32x32x16_f16 v[66:81], v[180:183], v[136:139], v[66:81]
	v_add_f32_e32 v126, v104, v126
	v_add_f32_e32 v126, v105, v126
	v_add_f32_e32 v126, v106, v126
	v_add_f32_e32 v126, v107, v126
	v_cvt_pk_f16_f32 v154, v102, v103
	v_cvt_pk_f16_f32 v155, v104, v105
	ds_read_b64_tr_b16 v[102:103], v192 offset:27648
	ds_read_b64_tr_b16 v[104:105], v192 offset:28160
	s_waitcnt lgkmcnt(14)
	v_mfma_f32_32x32x16_f16 v[82:97], v[184:187], v[132:135], v[82:97]
	v_add_f32_e32 v126, v108, v126
	v_add_f32_e32 v126, v109, v126
	v_add_f32_e32 v126, v110, v126
	v_add_f32_e32 v126, v111, v126
	v_cvt_pk_f16_f32 v148, v106, v107
	v_cvt_pk_f16_f32 v149, v108, v109
	ds_read_b64_tr_b16 v[106:107], v192 offset:31744
	ds_read_b64_tr_b16 v[108:109], v192 offset:32256
	v_mfma_f32_32x32x16_f16 v[66:81], v[50:53], v[132:135], v[66:81]
	v_add_f32_e32 v50, v112, v126
	v_add_f32_e32 v50, v113, v50
	v_add_f32_e32 v50, 0, v50
	v_cvt_pk_f16_f32 v150, v110, v111
	v_cvt_pk_f16_f32 v151, v112, v113
	v_lshl_add_u64 v[52:53], v[58:59], 0, s[48:49]
	s_add_i32 s42, s25, s97
	s_mov_b32 s44, m0
	s_mov_b32 m0, s42
	s_nop 0
	global_load_lds_dwordx4 v[52:53], off
	s_mov_b32 m0, s44
	v_lshl_add_u64 v[52:53], v[60:61], 0, s[52:53]
	s_add_i32 s42, s43, s83
	s_mov_b32 s44, m0
	s_mov_b32 m0, s42
	s_nop 0
	global_load_lds_dwordx4 v[52:53], off
	s_mov_b32 m0, s44
	v_add_f32_e32 v50, v0, v50
	s_waitcnt lgkmcnt(14)
	v_mfma_f32_32x32x16_f16 v[18:33], v[160:163], v[188:191], v[18:33]
	v_exp_f32_e32 v82, v82
	v_exp_f32_e32 v83, v83
	v_exp_f32_e32 v84, v84
	v_exp_f32_e32 v85, v85
	s_waitcnt lgkmcnt(12)
	v_mfma_f32_32x32x16_f16 v[34:49], v[160:163], v[62:65], v[34:49]
	v_exp_f32_e32 v86, v86
	v_exp_f32_e32 v87, v87
	v_exp_f32_e32 v88, v88
	v_exp_f32_e32 v89, v89
	v_add_u32_e32 v0, s43, v219
	ds_read_b128 v[192:195], v0
	ds_read_b128 v[188:191], v0 offset:512
	s_waitcnt lgkmcnt(12)
	v_mfma_f32_32x32x16_f16 v[18:33], v[156:159], v[114:117], v[18:33]
	v_exp_f32_e32 v90, v90
	v_exp_f32_e32 v91, v91
	v_exp_f32_e32 v92, v92
	v_exp_f32_e32 v93, v93
	ds_read_b128 v[184:187], v0 offset:2048
	ds_read_b128 v[180:183], v0 offset:2560
	s_waitcnt lgkmcnt(12)
	v_mfma_f32_32x32x16_f16 v[34:49], v[156:159], v[118:121], v[34:49]
	v_exp_f32_e32 v94, v94
	v_exp_f32_e32 v95, v95
	v_exp_f32_e32 v96, v96
	v_exp_f32_e32 v97, v97
	ds_read_b128 v[176:179], v0 offset:4096
	ds_read_b128 v[172:175], v0 offset:4608
	s_waitcnt lgkmcnt(12)
	v_mfma_f32_32x32x16_f16 v[18:33], v[152:155], v[122:125], v[18:33]
	v_exp_f32_e32 v66, v66
	v_exp_f32_e32 v67, v67
	v_exp_f32_e32 v68, v68
	v_exp_f32_e32 v69, v69
	ds_read_b128 v[168:171], v0 offset:6144
	ds_read_b128 v[164:167], v0 offset:6656
	s_waitcnt lgkmcnt(12)
	v_mfma_f32_32x32x16_f16 v[34:49], v[152:155], v[98:101], v[34:49]
	v_exp_f32_e32 v70, v70
	v_exp_f32_e32 v71, v71
	v_exp_f32_e32 v72, v72
	v_exp_f32_e32 v73, v73
	s_waitcnt lgkmcnt(10)
	v_mfma_f32_32x32x16_f16 v[18:33], v[148:151], v[102:105], v[18:33]
	v_exp_f32_e32 v74, v74
	v_exp_f32_e32 v75, v75
	v_exp_f32_e32 v76, v76
	v_exp_f32_e32 v77, v77
	s_waitcnt lgkmcnt(8)
	v_mfma_f32_32x32x16_f16 v[34:49], v[148:151], v[106:109], v[34:49]
	v_exp_f32_e32 v78, v78
	v_exp_f32_e32 v79, v79
	v_exp_f32_e32 v80, v80
	v_exp_f32_e32 v81, v81
	s_add_i32 s45, s43, 0x2000
	s_waitcnt vmcnt(2) lgkmcnt(8)
	s_barrier
	s_cmpk_lg_i32 s43, 0x4000
	s_mov_b32 s44, s25
	s_cselect_b32 s25, s45, 0
	s_add_i32 s24, s24, 2
	v_lshl_add_u64 v[54:55], v[54:55], 0, s[62:63]
	v_lshl_add_u64 v[56:57], v[56:57], 0, s[62:63]
	s_mov_b32 s42, s43
	s_cmp_lt_u32 s24, 29
	s_cbranch_scc1 .LBB0_77
	s_mov_b64 s[36:37], 0x10c84000
	s_mov_b64 s[60:61], 0x10388000
	s_mov_b32 s45, 31
	s_branch .LBB0_80
